# store-GEMM epilogue: bf16 stores without the nt hint (write-back in L2 acknowledges sooner; in-order vmcnt of the next tile's K-loop waits less)
# baseline (speedup 1.0000x reference)
; __device__ __forceinline__ void row_rstd8(const float* rsq, int row0, int fq, float (&rs)[8]) {
;     if (!rsq) {
; #pragma unroll
;         for (int i = 0; i < 8; ++i) rs[i] = 1.f;
;         return;
;     }
;     f32x4 p[8];
; #pragma unroll
;     for (int i = 0; i < 8; ++i) p[i] = *(const f32x4*)(rsq + (size_t)(row0 + (i >> 2) * 128 + (i & 3) * 16) * 16 + 4 * fq);
;     asm volatile("" ::: "memory");
; #pragma unroll
;     for (int i = 0; i < 8; ++i) rs[i] = rsqrtf(fq_sum((p[i].x + p[i].y) + (p[i].z + p[i].w)) * (1.f / DM) + 1e-6f);
; }
;     __device__ __forceinline__ void operator()(const pg8::f32x4 (&acc)[2][2][4][2], const pg8::Unit& u, int wr, int wc, int fr, int fq) const {
;         int oz; asm volatile("v_mov_b32 %0, 0" : "=v"(oz));
;         const int row0 = u.pm * 256 + wr * 64 + fr + oz, col0 = u.pn * 256 + wc * 32 + 8 * fq;
;         float rs8[8]; row_rstd8(rsq, row0, fq, rs8);
; #pragma unroll
;         for (int ai = 0; ai < 2; ++ai)
; #pragma unroll
;             for (int m = 0; m < 4; ++m) {
;                 bf16* p = O + (size_t)(row0 + ai * 128 + m * 16) * ldc + col0;
;                 const float r = rs8[ai * 4 + m];
.LBB0_523:
	s_lshl_b32 s8, s68, 8
	v_mov_b32 v130, 0
	s_mov_b32 s20, 0x3a800000
	v_add3_u32 v180, s8, v183, v130
	v_ashrrev_i32_e32 v181, 31, v180
	v_lshlrev_b64 v[130:131], 6, v[180:181]
	v_lshl_add_u64 v[130:131], v[160:161], 0, v[130:131]
	global_load_dwordx4 v[190:193], v[130:131], off
	v_add_u32_e32 v178, 16, v180
	v_ashrrev_i32_e32 v179, 31, v178
	v_lshlrev_b64 v[130:131], 6, v[178:179]
	v_lshl_add_u64 v[130:131], v[160:161], 0, v[130:131]
	global_load_dwordx4 v[194:197], v[130:131], off
	v_add_u32_e32 v176, 32, v180
	v_ashrrev_i32_e32 v177, 31, v176
	v_lshlrev_b64 v[130:131], 6, v[176:177]
	v_add_u32_e32 v174, 48, v180
	v_lshl_add_u64 v[130:131], v[160:161], 0, v[130:131]
	v_ashrrev_i32_e32 v175, 31, v174
	global_load_dwordx4 v[150:153], v[130:131], off
	v_lshlrev_b64 v[130:131], 6, v[174:175]
	v_lshl_add_u64 v[130:131], v[160:161], 0, v[130:131]
	global_load_dwordx4 v[146:149], v[130:131], off
	v_add_u32_e32 v172, 0x80, v180
	v_ashrrev_i32_e32 v173, 31, v172
	v_lshlrev_b64 v[130:131], 6, v[172:173]
	v_add_u32_e32 v170, 0x90, v180
	v_lshl_add_u64 v[130:131], v[160:161], 0, v[130:131]
	v_ashrrev_i32_e32 v171, 31, v170
	global_load_dwordx4 v[142:145], v[130:131], off
	v_lshlrev_b64 v[130:131], 6, v[170:171]
	v_lshl_add_u64 v[130:131], v[160:161], 0, v[130:131]
	global_load_dwordx4 v[138:141], v[130:131], off
	v_add_u32_e32 v168, 0xa0, v180
	v_ashrrev_i32_e32 v169, 31, v168
	v_lshlrev_b64 v[130:131], 6, v[168:169]
	v_add_u32_e32 v166, 0xb0, v180
	v_lshl_add_u64 v[130:131], v[160:161], 0, v[130:131]
	v_ashrrev_i32_e32 v167, 31, v166
	global_load_dwordx4 v[134:137], v[130:131], off
	v_lshlrev_b64 v[130:131], 6, v[166:167]
	v_lshl_add_u64 v[130:131], v[160:161], 0, v[130:131]
	global_load_dwordx4 v[130:133], v[130:131], off
	s_mov_b32 s8, 0x358637bd
	s_waitcnt vmcnt(0)
	v_mov_b32_e32 v186, v191
	v_mov_b32_e32 v187, v192
	v_mov_b32_e32 v191, v193
	v_pk_add_f32 v[186:187], v[186:187], v[190:191]
	v_mov_b32_e32 v192, v195
	v_add_f32_e32 v167, v186, v187
	ds_swizzle_b32 v169, v167 offset:swizzle(SWAP,16)
	v_mov_b32_e32 v193, v196
	v_mov_b32_e32 v195, v197
	v_pk_add_f32 v[192:193], v[192:193], v[194:195]
	s_waitcnt lgkmcnt(0)
	v_add_f32_e32 v187, v167, v169
	v_add_f32_e32 v167, v192, v193
	ds_swizzle_b32 v169, v167 offset:swizzle(SWAP,16)
	v_mov_b32_e32 v191, v187
	s_nop 1
	v_permlane32_swap_b32_e32 v187, v191
	s_waitcnt lgkmcnt(0)
	v_add_f32_e32 v186, v167, v169
	v_mov_b32_e32 v190, v186
	s_nop 1
	v_permlane32_swap_b32_e32 v186, v190
	v_pk_add_f32 v[190:191], v[186:187], v[190:191]
	v_mov_b64_e32 v[186:187], s[8:9]
	v_pk_fma_f32 v[190:191], v[190:191], s[20:21], v[186:187] op_sel_hi:[1,0,0]
	s_nop 0
	v_mul_f32_e32 v167, 0x4b800000, v191
	v_cmp_gt_f32_e64 s[8:9], s37, v191
	v_cmp_gt_f32_e32 vcc, s37, v190
	s_nop 0
	v_cndmask_b32_e64 v167, v191, v167, s[8:9]
	v_rsq_f32_e32 v167, v167
	v_mov_b32_e32 v191, v152
	v_mul_f32_e32 v169, 0x45800000, v167
	v_cndmask_b32_e64 v184, v167, v169, s[8:9]
	v_mul_f32_e32 v167, 0x4b800000, v190
	v_cndmask_b32_e32 v167, v190, v167, vcc
	v_mov_b32_e32 v190, v151
	v_mov_b32_e32 v151, v153
	v_pk_add_f32 v[150:151], v[190:191], v[150:151]
	v_mov_b32_e32 v190, v147
	v_mov_b32_e32 v191, v148
	v_mov_b32_e32 v147, v149
	v_pk_add_f32 v[146:147], v[190:191], v[146:147]
	v_add_f32_e32 v150, v150, v151
	v_add_f32_e32 v146, v146, v147
	ds_swizzle_b32 v151, v150 offset:swizzle(SWAP,16)
	ds_swizzle_b32 v147, v146 offset:swizzle(SWAP,16)
	v_rsq_f32_e32 v167, v167
	v_pk_mul_f32 v[118:119], v[118:119], v[184:185] op_sel_hi:[1,0]
	v_pk_mul_f32 v[120:121], v[120:121], v[184:185] op_sel_hi:[1,0]
	s_waitcnt lgkmcnt(1)
	v_add_f32_e32 v151, v150, v151
	s_waitcnt lgkmcnt(0)
	v_add_f32_e32 v150, v146, v147
	v_mov_b32_e32 v153, v151
	v_mov_b32_e32 v152, v150
	s_nop 0
	v_permlane32_swap_b32_e32 v151, v153
	v_permlane32_swap_b32_e32 v150, v152
	v_pk_add_f32 v[146:147], v[150:151], v[152:153]
	v_mov_b32_e32 v150, v143
	v_mov_b32_e32 v151, v144
	v_mov_b32_e32 v143, v145
	v_pk_add_f32 v[142:143], v[150:151], v[142:143]
	v_mov_b32_e32 v150, v139
	v_mov_b32_e32 v151, v140
	v_mov_b32_e32 v139, v141
	v_pk_add_f32 v[138:139], v[150:151], v[138:139]
	v_add_f32_e32 v142, v142, v143
	v_add_f32_e32 v138, v138, v139
	ds_swizzle_b32 v143, v142 offset:swizzle(SWAP,16)
	ds_swizzle_b32 v139, v138 offset:swizzle(SWAP,16)
	v_pk_fma_f32 v[148:149], v[146:147], s[20:21], v[186:187] op_sel_hi:[1,0,0]
	v_mul_f32_e32 v169, 0x45800000, v167
	v_mul_f32_e32 v146, 0x4b800000, v149
	s_waitcnt lgkmcnt(1)
	v_add_f32_e32 v143, v142, v143
	s_waitcnt lgkmcnt(0)
	v_add_f32_e32 v142, v138, v139
	v_mov_b32_e32 v145, v143
	v_mov_b32_e32 v144, v142
	s_nop 0
	v_permlane32_swap_b32_e32 v143, v145
	v_permlane32_swap_b32_e32 v142, v144
	v_cmp_gt_f32_e64 s[8:9], s37, v149
	v_pk_add_f32 v[138:139], v[142:143], v[144:145]
	v_mov_b32_e32 v142, v135
	v_mov_b32_e32 v143, v136
	v_mov_b32_e32 v135, v137
	v_cndmask_b32_e64 v146, v149, v146, s[8:9]
	v_pk_add_f32 v[134:135], v[142:143], v[134:135]
	v_mov_b32_e32 v142, v131
	v_mov_b32_e32 v143, v132
	v_mov_b32_e32 v131, v133
	v_rsq_f32_e32 v146, v146
	v_pk_add_f32 v[130:131], v[142:143], v[130:131]
	v_add_f32_e32 v134, v134, v135
	v_add_f32_e32 v130, v130, v131
	ds_swizzle_b32 v135, v134 offset:swizzle(SWAP,16)
	ds_swizzle_b32 v131, v130 offset:swizzle(SWAP,16)
	v_mul_f32_e32 v147, 0x45800000, v146
	v_pk_fma_f32 v[138:139], v[138:139], s[20:21], v[186:187] op_sel_hi:[1,0,0]
	v_cndmask_b32_e32 v182, v167, v169, vcc
	v_cmp_gt_f32_e32 vcc, s37, v148
	v_cndmask_b32_e64 v146, v146, v147, s[8:9]
	v_mul_f32_e32 v147, 0x4b800000, v148
	v_mul_f32_e32 v140, 0x4b800000, v139
	v_cmp_gt_f32_e64 s[8:9], s37, v139
	v_cndmask_b32_e32 v147, v148, v147, vcc
	v_rsq_f32_e32 v147, v147
	v_cndmask_b32_e64 v139, v139, v140, s[8:9]
	v_rsq_f32_e32 v139, v139
	s_waitcnt lgkmcnt(1)
; __device__ __forceinline__ unsigned pk2(float lo, float hi) { f32x2 v = {lo, hi}; bf16x2_t b = __builtin_convertvector(v, bf16x2_t); return __builtin_bit_cast(unsigned, b); }
; __device__ __forceinline__ void row_rstd8(const float* rsq, int row0, int fq, float (&rs)[8]) {
;     ...
;     for (int i = 0; i < 8; ++i) rs[i] = rsqrtf(fq_sum((p[i].x + p[i].y) + (p[i].z + p[i].w)) * (1.f / DM) + 1e-6f);
;     __device__ __forceinline__ void operator()(const pg8::f32x4 (&acc)[2][2][4][2], const pg8::Unit& u, int wr, int wc, int fr, int fq) const {
;     ...
;                 bf16* p = O + (size_t)(row0 + ai * 128 + m * 16) * ldc + col0;
;                 const float r = rs8[ai * 4 + m];
; #pragma unroll
;                 for (int bj = 0; bj < 2; ++bj) {
;                     u32x4 w; w.x = pk2(acc[ai][bj][m][0][0] * r, acc[ai][bj][m][0][1] * r); w.y = pk2(acc[ai][bj][m][0][2] * r, acc[ai][bj][m][0][3] * r);
;                     w.z = pk2(acc[ai][bj][m][1][0] * r, acc[ai][bj][m][1][1] * r); w.w = pk2(acc[ai][bj][m][1][2] * r, acc[ai][bj][m][1][3] * r);
	v_add_f32_e32 v135, v134, v135
	s_waitcnt lgkmcnt(0)
	v_add_f32_e32 v134, v130, v131
	v_mov_b32_e32 v137, v135
	v_mov_b32_e32 v136, v134
	s_nop 0
	v_permlane32_swap_b32_e32 v135, v137
	v_permlane32_swap_b32_e32 v134, v136
	v_pk_add_f32 v[130:131], v[134:135], v[136:137]
	v_mul_f32_e32 v148, 0x45800000, v147
	v_mul_f32_e32 v140, 0x45800000, v139
	v_pk_fma_f32 v[130:131], v[130:131], s[20:21], v[186:187] op_sel_hi:[1,0,0]
	v_cndmask_b32_e32 v148, v147, v148, vcc
	v_cmp_gt_f32_e32 vcc, s37, v138
	v_cndmask_b32_e64 v140, v139, v140, s[8:9]
	v_mul_f32_e32 v139, 0x4b800000, v138
	v_mul_f32_e32 v132, 0x4b800000, v131
	v_cmp_gt_f32_e64 s[8:9], s37, v131
	v_cndmask_b32_e32 v138, v138, v139, vcc
	v_rsq_f32_e32 v138, v138
	v_cndmask_b32_e64 v131, v131, v132, s[8:9]
	v_rsq_f32_e32 v131, v131
	v_pk_mul_f32 v[114:115], v[114:115], v[184:185] op_sel_hi:[1,0]
	v_mul_f32_e32 v139, 0x45800000, v138
	v_cndmask_b32_e32 v138, v138, v139, vcc
	v_mul_f32_e32 v132, 0x45800000, v131
	v_cmp_gt_f32_e32 vcc, s37, v130
	v_cndmask_b32_e64 v132, v131, v132, s[8:9]
	v_mul_f32_e32 v131, 0x4b800000, v130
	v_cndmask_b32_e32 v130, v130, v131, vcc
	v_rsq_f32_e32 v130, v130
	v_pk_mul_f32 v[102:103], v[102:103], v[182:183] op_sel_hi:[1,0]
	v_pk_mul_f32 v[104:105], v[104:105], v[182:183] op_sel_hi:[1,0]
	v_pk_mul_f32 v[98:99], v[98:99], v[182:183] op_sel_hi:[1,0]
	v_mul_f32_e32 v131, 0x45800000, v130
	v_pk_mul_f32 v[86:87], v[86:87], v[146:147] op_sel_hi:[1,0]
	v_pk_mul_f32 v[88:89], v[88:89], v[146:147] op_sel_hi:[1,0]
	v_pk_mul_f32 v[82:83], v[82:83], v[146:147] op_sel_hi:[1,0]
	v_pk_mul_f32 v[70:71], v[70:71], v[148:149] op_sel_hi:[1,0]
	v_pk_mul_f32 v[72:73], v[72:73], v[148:149] op_sel_hi:[1,0]
	v_pk_mul_f32 v[66:67], v[66:67], v[148:149] op_sel_hi:[1,0]
	v_pk_mul_f32 v[54:55], v[54:55], v[140:141] op_sel_hi:[1,0]
	v_pk_mul_f32 v[56:57], v[56:57], v[140:141] op_sel_hi:[1,0]
	v_pk_mul_f32 v[50:51], v[50:51], v[140:141] op_sel_hi:[1,0]
	v_pk_mul_f32 v[38:39], v[38:39], v[138:139] op_sel_hi:[1,0]
	v_pk_mul_f32 v[40:41], v[40:41], v[138:139] op_sel_hi:[1,0]
	v_pk_mul_f32 v[34:35], v[34:35], v[138:139] op_sel_hi:[1,0]
	v_pk_mul_f32 v[22:23], v[22:23], v[132:133] op_sel_hi:[1,0]
	v_pk_mul_f32 v[24:25], v[24:25], v[132:133] op_sel_hi:[1,0]
	v_pk_mul_f32 v[18:19], v[18:19], v[132:133] op_sel_hi:[1,0]
	v_cndmask_b32_e32 v130, v130, v131, vcc
	v_lshl_or_b32 v134, s67, 8, v188
	v_cvt_pk_bf16_f32 v118, v118, v119
	v_cvt_pk_bf16_f32 v119, v120, v121
	v_cvt_pk_bf16_f32 v120, v114, v115
	v_pk_mul_f32 v[114:115], v[116:117], v[184:185] op_sel_hi:[1,0]
	v_cvt_pk_bf16_f32 v102, v102, v103
	v_cvt_pk_bf16_f32 v103, v104, v105
	v_cvt_pk_bf16_f32 v104, v98, v99
	v_pk_mul_f32 v[98:99], v[100:101], v[182:183] op_sel_hi:[1,0]
	v_cvt_pk_bf16_f32 v86, v86, v87
	v_cvt_pk_bf16_f32 v87, v88, v89
	v_cvt_pk_bf16_f32 v88, v82, v83
	v_pk_mul_f32 v[82:83], v[84:85], v[146:147] op_sel_hi:[1,0]
	v_cvt_pk_bf16_f32 v70, v70, v71
	v_cvt_pk_bf16_f32 v71, v72, v73
	v_cvt_pk_bf16_f32 v72, v66, v67
	v_pk_mul_f32 v[66:67], v[68:69], v[148:149] op_sel_hi:[1,0]
	v_cvt_pk_bf16_f32 v54, v54, v55
	v_cvt_pk_bf16_f32 v55, v56, v57
	v_cvt_pk_bf16_f32 v56, v50, v51
	v_pk_mul_f32 v[50:51], v[52:53], v[140:141] op_sel_hi:[1,0]
	v_cvt_pk_bf16_f32 v38, v38, v39
	v_cvt_pk_bf16_f32 v39, v40, v41
	v_cvt_pk_bf16_f32 v40, v34, v35
	v_pk_mul_f32 v[34:35], v[36:37], v[138:139] op_sel_hi:[1,0]
	v_cvt_pk_bf16_f32 v22, v22, v23
	v_cvt_pk_bf16_f32 v23, v24, v25
	v_cvt_pk_bf16_f32 v24, v18, v19
	v_pk_mul_f32 v[18:19], v[20:21], v[132:133] op_sel_hi:[1,0]
	v_ashrrev_i32_e32 v135, 31, v134
	v_mad_i64_i32 v[136:137], s[8:9], v180, s2, 0
	v_pk_mul_f32 v[126:127], v[126:127], v[184:185] op_sel_hi:[1,0]
	v_pk_mul_f32 v[128:129], v[128:129], v[184:185] op_sel_hi:[1,0]
	v_pk_mul_f32 v[122:123], v[122:123], v[184:185] op_sel_hi:[1,0]
	v_cvt_pk_bf16_f32 v121, v114, v115
	v_mad_i64_i32 v[114:115], s[8:9], v178, s2, 0
	v_pk_mul_f32 v[110:111], v[110:111], v[182:183] op_sel_hi:[1,0]
	v_pk_mul_f32 v[112:113], v[112:113], v[182:183] op_sel_hi:[1,0]
	v_pk_mul_f32 v[106:107], v[106:107], v[182:183] op_sel_hi:[1,0]
	v_cvt_pk_bf16_f32 v105, v98, v99
	v_mad_i64_i32 v[98:99], s[8:9], v176, s2, 0
	v_pk_mul_f32 v[94:95], v[94:95], v[146:147] op_sel_hi:[1,0]
	v_pk_mul_f32 v[96:97], v[96:97], v[146:147] op_sel_hi:[1,0]
	v_pk_mul_f32 v[90:91], v[90:91], v[146:147] op_sel_hi:[1,0]
	v_cvt_pk_bf16_f32 v89, v82, v83
	v_mad_i64_i32 v[82:83], s[8:9], v174, s2, 0
	v_pk_mul_f32 v[78:79], v[78:79], v[148:149] op_sel_hi:[1,0]
	v_pk_mul_f32 v[80:81], v[80:81], v[148:149] op_sel_hi:[1,0]
	v_pk_mul_f32 v[74:75], v[74:75], v[148:149] op_sel_hi:[1,0]
	v_cvt_pk_bf16_f32 v73, v66, v67
	v_mad_i64_i32 v[66:67], s[8:9], v172, s2, 0
	v_pk_mul_f32 v[62:63], v[62:63], v[140:141] op_sel_hi:[1,0]
; __device__ __forceinline__ unsigned pk2(float lo, float hi) { f32x2 v = {lo, hi}; bf16x2_t b = __builtin_convertvector(v, bf16x2_t); return __builtin_bit_cast(unsigned, b); }
;     __device__ __forceinline__ void operator()(const pg8::f32x4 (&acc)[2][2][4][2], const pg8::Unit& u, int wr, int wc, int fr, int fq) const {
;     ...
;                 bf16* p = O + (size_t)(row0 + ai * 128 + m * 16) * ldc + col0;
;                 const float r = rs8[ai * 4 + m];
; #pragma unroll
;                 for (int bj = 0; bj < 2; ++bj) {
;                     u32x4 w; w.x = pk2(acc[ai][bj][m][0][0] * r, acc[ai][bj][m][0][1] * r); w.y = pk2(acc[ai][bj][m][0][2] * r, acc[ai][bj][m][0][3] * r);
;                     w.z = pk2(acc[ai][bj][m][1][0] * r, acc[ai][bj][m][1][1] * r); w.w = pk2(acc[ai][bj][m][1][2] * r, acc[ai][bj][m][1][3] * r);
;                     __builtin_nontemporal_store(w, (u32x4*)(p + bj * 128));
	v_pk_mul_f32 v[64:65], v[64:65], v[140:141] op_sel_hi:[1,0]
	v_pk_mul_f32 v[58:59], v[58:59], v[140:141] op_sel_hi:[1,0]
	v_cvt_pk_bf16_f32 v57, v50, v51
	v_mad_i64_i32 v[50:51], s[8:9], v170, s2, 0
	v_pk_mul_f32 v[46:47], v[46:47], v[138:139] op_sel_hi:[1,0]
	v_pk_mul_f32 v[48:49], v[48:49], v[138:139] op_sel_hi:[1,0]
	v_pk_mul_f32 v[42:43], v[42:43], v[138:139] op_sel_hi:[1,0]
	v_cvt_pk_bf16_f32 v41, v34, v35
	v_mad_i64_i32 v[34:35], s[8:9], v168, s2, 0
	v_pk_mul_f32 v[30:31], v[30:31], v[132:133] op_sel_hi:[1,0]
	v_pk_mul_f32 v[32:33], v[32:33], v[132:133] op_sel_hi:[1,0]
	v_pk_mul_f32 v[26:27], v[26:27], v[132:133] op_sel_hi:[1,0]
	v_cvt_pk_bf16_f32 v25, v18, v19
	v_mad_i64_i32 v[18:19], s[8:9], v166, s2, 0
	v_pk_mul_f32 v[14:15], v[14:15], v[130:131] op_sel_hi:[1,0]
	v_pk_mul_f32 v[16:17], v[16:17], v[130:131] op_sel_hi:[1,0]
	v_pk_mul_f32 v[10:11], v[10:11], v[130:131] op_sel_hi:[1,0]
	v_pk_mul_f32 v[6:7], v[6:7], v[130:131] op_sel_hi:[1,0]
	v_pk_mul_f32 v[8:9], v[8:9], v[130:131] op_sel_hi:[1,0]
	v_pk_mul_f32 v[2:3], v[2:3], v[130:131] op_sel_hi:[1,0]
	v_lshl_add_u64 v[136:137], v[136:137], 1, s[28:29]
	v_lshlrev_b64 v[134:135], 1, v[134:135]
	v_cvt_pk_bf16_f32 v126, v126, v127
	v_cvt_pk_bf16_f32 v127, v128, v129
	v_cvt_pk_bf16_f32 v128, v122, v123
	v_pk_mul_f32 v[122:123], v[124:125], v[184:185] op_sel_hi:[1,0]
	v_lshl_add_u64 v[114:115], v[114:115], 1, s[28:29]
	v_cvt_pk_bf16_f32 v110, v110, v111
	v_cvt_pk_bf16_f32 v111, v112, v113
	v_cvt_pk_bf16_f32 v112, v106, v107
	v_pk_mul_f32 v[106:107], v[108:109], v[182:183] op_sel_hi:[1,0]
	v_lshl_add_u64 v[98:99], v[98:99], 1, s[28:29]
	v_cvt_pk_bf16_f32 v94, v94, v95
	v_cvt_pk_bf16_f32 v95, v96, v97
	v_cvt_pk_bf16_f32 v96, v90, v91
	v_pk_mul_f32 v[90:91], v[92:93], v[146:147] op_sel_hi:[1,0]
	v_lshl_add_u64 v[82:83], v[82:83], 1, s[28:29]
	v_cvt_pk_bf16_f32 v78, v78, v79
	v_cvt_pk_bf16_f32 v79, v80, v81
	v_cvt_pk_bf16_f32 v80, v74, v75
	v_pk_mul_f32 v[74:75], v[76:77], v[148:149] op_sel_hi:[1,0]
	v_lshl_add_u64 v[66:67], v[66:67], 1, s[28:29]
	v_cvt_pk_bf16_f32 v62, v62, v63
	v_cvt_pk_bf16_f32 v63, v64, v65
	v_cvt_pk_bf16_f32 v64, v58, v59
	v_pk_mul_f32 v[58:59], v[60:61], v[140:141] op_sel_hi:[1,0]
	v_lshl_add_u64 v[50:51], v[50:51], 1, s[28:29]
	v_cvt_pk_bf16_f32 v46, v46, v47
	v_cvt_pk_bf16_f32 v47, v48, v49
	v_cvt_pk_bf16_f32 v48, v42, v43
	v_pk_mul_f32 v[42:43], v[44:45], v[138:139] op_sel_hi:[1,0]
	v_lshl_add_u64 v[34:35], v[34:35], 1, s[28:29]
	v_cvt_pk_bf16_f32 v30, v30, v31
	v_cvt_pk_bf16_f32 v31, v32, v33
	v_cvt_pk_bf16_f32 v32, v26, v27
	v_pk_mul_f32 v[26:27], v[28:29], v[132:133] op_sel_hi:[1,0]
	v_lshl_add_u64 v[18:19], v[18:19], 1, s[28:29]
	v_cvt_pk_bf16_f32 v14, v14, v15
	v_cvt_pk_bf16_f32 v15, v16, v17
	v_cvt_pk_bf16_f32 v16, v10, v11
	v_pk_mul_f32 v[10:11], v[12:13], v[130:131] op_sel_hi:[1,0]
	v_cvt_pk_bf16_f32 v6, v6, v7
	v_cvt_pk_bf16_f32 v7, v8, v9
	v_cvt_pk_bf16_f32 v8, v2, v3
	v_pk_mul_f32 v[2:3], v[4:5], v[130:131] op_sel_hi:[1,0]
	v_lshl_add_u64 v[136:137], v[136:137], 0, v[134:135]
	v_cvt_pk_bf16_f32 v129, v122, v123
	v_lshl_add_u64 v[114:115], v[114:115], 0, v[134:135]
	v_cvt_pk_bf16_f32 v113, v106, v107
	v_lshl_add_u64 v[98:99], v[98:99], 0, v[134:135]
	v_cvt_pk_bf16_f32 v97, v90, v91
	v_lshl_add_u64 v[82:83], v[82:83], 0, v[134:135]
	v_cvt_pk_bf16_f32 v81, v74, v75
	v_lshl_add_u64 v[66:67], v[66:67], 0, v[134:135]
	v_cvt_pk_bf16_f32 v65, v58, v59
	v_lshl_add_u64 v[50:51], v[50:51], 0, v[134:135]
	v_cvt_pk_bf16_f32 v49, v42, v43
	v_lshl_add_u64 v[34:35], v[34:35], 0, v[134:135]
	v_cvt_pk_bf16_f32 v33, v26, v27
	v_lshl_add_u64 v[18:19], v[18:19], 0, v[134:135]
	v_cvt_pk_bf16_f32 v17, v10, v11
	v_cvt_pk_bf16_f32 v9, v2, v3
	s_mov_b64 s[8:9], -1
	s_and_b64 vcc, exec, s[6:7]
	global_store_dwordx4 v[136:137], v[126:129], off
	global_store_dwordx4 v[136:137], v[118:121], off offset:256
	global_store_dwordx4 v[114:115], v[110:113], off
	global_store_dwordx4 v[114:115], v[102:105], off offset:256
	global_store_dwordx4 v[98:99], v[94:97], off
	global_store_dwordx4 v[98:99], v[86:89], off offset:256
	global_store_dwordx4 v[82:83], v[78:81], off
	global_store_dwordx4 v[82:83], v[70:73], off offset:256
	global_store_dwordx4 v[66:67], v[62:65], off
	global_store_dwordx4 v[66:67], v[54:57], off offset:256
	global_store_dwordx4 v[50:51], v[46:49], off
	global_store_dwordx4 v[50:51], v[38:41], off offset:256
	global_store_dwordx4 v[34:35], v[30:33], off
	global_store_dwordx4 v[34:35], v[22:25], off offset:256
	global_store_dwordx4 v[18:19], v[14:17], off
	global_store_dwordx4 v[18:19], v[6:9], off offset:256
	s_cbranch_vccnz .LBB0_511
	s_andn2_b64 vcc, exec, s[42:43]
	s_cbranch_vccnz .LBB0_510
	s_barrier
	s_branch .LBB0_510
